# v63 + attention phase: one static s_setprio 1 for waves 4-7 at phase entry (reset to 0 at phase exit)
# speedup vs baseline: 1.0014x; 1.0014x over previous
.LBB0_892:
	s_cmp_lt_i32 s64, 11
	s_cselect_b64 s[14:15], -1, 0
	s_and_b64 s[2:3], s[14:15], s[2:3]
	s_andn2_b64 vcc, exec, s[2:3]
	v_mbcnt_lo_u32_b32 v252, -1, 0
	s_cbranch_vccnz .LBB0_1043
	s_cmp_ge_u32 s1, 4
	s_cbranch_scc0 .Lattn_prio_done
	s_setprio 1
.Lattn_prio_done:
	s_mov_b32 s16, s1
	s_mov_b32 s2, s76
	s_waitcnt lgkmcnt(0)
	s_mov_b32 s6, s28
	v_readlane_b32 s22, v255, 2
	s_waitcnt vmcnt(0)
	v_mbcnt_lo_u32_b32 v0, -1, 0
	v_mbcnt_hi_u32_b32 v0, -1, v0
	v_readlane_b32 s23, v255, 3
	s_mov_b64 s[2:3], s[22:23]
	s_mov_b64 s[4:5], s[22:23]
	s_load_dwordx2 s[2:3], s[2:3], 0xf0
	s_load_dwordx2 s[10:11], s[4:5], 0xf0
	s_mov_b64 s[4:5], s[22:23]
	s_mov_b64 s[8:9], s[22:23]
	s_load_dwordx2 s[4:5], s[4:5], 0xf0
	s_mov_b64 s[12:13], s[22:23]
	s_load_dwordx2 s[8:9], s[8:9], 0xf0
	s_load_dwordx2 s[12:13], s[12:13], 0x90
	v_and_b32_e32 v239, 63, v0
	v_lshlrev_b32_e32 v1, 2, v239
	s_waitcnt lgkmcnt(0)
	global_load_dword v2, v1, s[12:13]
	global_load_dword v3, v1, s[12:13] offset:256
	global_load_dword v4, v1, s[12:13] offset:512
	global_load_dword v5, v1, s[12:13] offset:768
	v_mbcnt_hi_u32_b32 v6, -1, v252
	v_and_b32_e32 v9, 64, v6
	v_xor_b32_e32 v10, 1, v6
	v_add_u32_e32 v9, 64, v9
	v_xor_b32_e32 v11, 2, v6
	v_cmp_lt_i32_e32 vcc, v10, v9
	v_xor_b32_e32 v12, 4, v6
	v_xor_b32_e32 v13, 8, v6
	v_cndmask_b32_e32 v10, v6, v10, vcc
	v_cmp_lt_i32_e32 vcc, v11, v9
	v_lshlrev_b32_e32 v241, 2, v10
	v_xor_b32_e32 v14, 16, v6
	v_cndmask_b32_e32 v11, v6, v11, vcc
	v_lshlrev_b32_e32 v242, 2, v11
	v_cmp_lt_i32_e32 vcc, v12, v9
	v_xor_b32_e32 v15, 32, v6
	s_ashr_i32 s17, s76, 31
	v_cndmask_b32_e32 v12, v6, v12, vcc
	v_lshlrev_b32_e32 v243, 2, v12
	v_cmp_lt_i32_e32 vcc, v13, v9
	s_lshr_b32 s17, s17, 29
	s_add_i32 s17, s76, s17
	v_cndmask_b32_e32 v13, v6, v13, vcc
	v_cmp_lt_i32_e32 vcc, v14, v9
	v_lshl_add_u32 v240, s16, 6, v0
	s_ashr_i32 s16, s17, 3
	v_cndmask_b32_e32 v14, v6, v14, vcc
	v_cmp_lt_i32_e32 vcc, v15, v9
	v_lshlrev_b32_e32 v9, 2, v13
	v_lshlrev_b32_e32 v12, 2, v14
	v_cndmask_b32_e32 v6, v6, v15, vcc
	v_lshlrev_b32_e32 v6, 2, v6
	s_and_b32 s17, s17, -8
	s_mov_b32 s18, 0x3fb8aa3b
	s_sub_i32 s17, s76, s17
	s_add_u32 s58, s2, 0x11200000
	s_addc_u32 s59, s3, 0
	s_add_u32 s60, s10, 0x15300000
	s_addc_u32 s61, s11, 0
	s_add_u32 s62, s4, 0x19400000
	s_addc_u32 s63, s5, 0
	s_mov_b32 s19, 0xc2ce8ed0
	s_add_u32 s64, s8, 0x29800000
	s_mov_b64 s[12:13], s[22:23]
	s_addc_u32 s65, s9, 0
	s_ashr_i32 s8, s6, 31
	s_mov_b32 s20, 0x42b17218
	s_load_dwordx2 s[2:3], s[12:13], 0xf0
	s_lshr_b32 s8, s8, 29
	v_mov_b32_e32 v7, 0x7f800000
	s_add_i32 s6, s6, s8
	s_ashr_i32 s6, s6, 3
	s_mul_i32 s6, s6, s17
	s_add_i32 s6, s6, s16
	v_mov_b32_e32 v8, 0x3eb60549
	s_waitcnt lgkmcnt(0)
	s_add_u32 s66, s2, 0x35b00000
	s_addc_u32 s67, s3, 0
	s_cmp_lg_u32 0, -1
	v_and_b32_e32 v244, 31, v0
	v_bfe_u32 v245, v0, 2, 4
	v_mov_b32_e32 v1, 0
	s_mov_b32 s7, 0
	s_mov_b64 s[10:11], 0x80
	s_mov_b64 s[12:13], 0x20000
	s_mov_b64 s[16:17], 0x40000
	s_mov_b64 s[24:25], 0x19440000
	s_mov_b64 s[26:27], 0x19440080
	s_mov_b32 s73, 0x41000000
	s_mov_b64 s[36:37], 0xa0000
	s_mov_b64 s[38:39], 0x19460000
	s_mov_b64 s[40:41], 0x19460080
	s_mov_b64 s[42:43], 0x19420000
	s_mov_b64 s[44:45], 0x19420080
	s_mov_b32 s74, 0xf800000
	v_mov_b32_e32 v254, 0x260
	s_mov_b32 s75, 0x3f24fd5c
	s_waitcnt vmcnt(2)
	v_mul_f32_e32 v10, v2, v3
	ds_bpermute_b32 v10, v241, v10
	s_waitcnt vmcnt(0)
	v_mul_f32_e32 v11, v4, v5
	ds_bpermute_b32 v11, v241, v11
	v_mov_b32_e32 v238, 0xff800000
	s_mov_b32 s80, 0
	s_waitcnt lgkmcnt(1)
	v_fmac_f32_e32 v10, v2, v3
	ds_bpermute_b32 v2, v242, v10
	s_waitcnt lgkmcnt(1)
	v_fmac_f32_e32 v11, v4, v5
	ds_bpermute_b32 v3, v242, v11
	s_waitcnt lgkmcnt(1)
	v_add_f32_e32 v2, v10, v2
	ds_bpermute_b32 v4, v243, v2
	s_waitcnt lgkmcnt(1)
	v_add_f32_e32 v3, v11, v3
	ds_bpermute_b32 v5, v243, v3
	s_waitcnt lgkmcnt(1)
	v_add_f32_e32 v2, v2, v4
	ds_bpermute_b32 v4, v9, v2
	s_waitcnt lgkmcnt(1)
	v_add_f32_e32 v3, v3, v5
	ds_bpermute_b32 v5, v9, v3
	s_waitcnt lgkmcnt(1)
	v_add_f32_e32 v2, v2, v4
	ds_bpermute_b32 v4, v12, v2
	s_waitcnt lgkmcnt(1)
	v_add_f32_e32 v3, v3, v5
	ds_bpermute_b32 v5, v12, v3
	s_waitcnt lgkmcnt(1)
	v_add_f32_e32 v2, v2, v4
	ds_bpermute_b32 v4, v6, v2
	s_waitcnt lgkmcnt(1)
	v_add_f32_e32 v3, v3, v5
	ds_bpermute_b32 v5, v6, v3
	s_waitcnt lgkmcnt(1)
	v_add_f32_e32 v2, v2, v4
	v_mul_f32_e32 v4, 0x3fb8aa3b, v2
	s_waitcnt lgkmcnt(0)
	v_add_f32_e32 v3, v3, v5
	v_mul_f32_e32 v5, 0x3fb8aa3b, v3
	v_fma_f32 v6, v2, s18, -v4
	v_rndne_f32_e32 v9, v4
	v_fma_f32 v10, v3, s18, -v5
	v_rndne_f32_e32 v11, v5
	v_fmac_f32_e32 v6, 0x32a5705f, v2
	v_sub_f32_e32 v4, v4, v9
	v_fmac_f32_e32 v10, 0x32a5705f, v3
	v_sub_f32_e32 v5, v5, v11
	v_add_f32_e32 v4, v4, v6
	v_cvt_i32_f32_e32 v9, v9
	v_add_f32_e32 v5, v5, v10
	v_exp_f32_e32 v4, v4
	v_cvt_i32_f32_e32 v11, v11
	v_exp_f32_e32 v5, v5
	v_cmp_ngt_f32_e32 vcc, s19, v2
	v_ldexp_f32 v4, v4, v9
	v_lshlrev_b32_e32 v6, 4, v0
	v_ldexp_f32 v5, v5, v11
	v_cndmask_b32_e32 v4, 0, v4, vcc
	v_cmp_ngt_f32_e32 vcc, s19, v3
	v_and_b32_e32 v6, 0xc0, v6
	v_lshlrev_b32_e32 v10, 4, v244
	v_cndmask_b32_e32 v5, 0, v5, vcc
	v_cmp_nlt_f32_e32 vcc, s20, v2
	s_mov_b64 s[18:19], 0x60000
	s_nop 0
	v_cndmask_b32_e32 v2, v7, v4, vcc
	v_cmp_nlt_f32_e32 vcc, s20, v3
	v_lshlrev_b32_e32 v4, 3, v0
	v_and_b32_e32 v4, 24, v4
	v_cndmask_b32_e32 v3, v7, v5, vcc
	v_sub_f32_e32 v2, v2, v3
	v_bfe_u32 v3, v0, 5, 1
	v_readfirstlane_b32 s2, v2
	v_lshlrev_b32_e32 v5, 1, v0
	v_and_b32_e32 v5, 32, v5
	v_add_f32_e32 v224, s2, v8
	s_mov_b64 s[2:3], s[22:23]
	s_load_dwordx2 s[8:9], s[2:3], 0x98
	s_cselect_b32 s2, 0, 0
	s_addk_i32 s2, 0x6000
	v_lshl_or_b32 v8, v3, 8, v6
	v_lshlrev_b32_e32 v6, 10, v244
	v_and_b32_e32 v0, 3, v0
	v_lshlrev_b32_e32 v2, 10, v239
	v_add_u32_e32 v7, s2, v5
	v_lshlrev_b32_e32 v9, 10, v3
	v_add_u32_e32 v5, 0, v5
	s_and_b32 s68, s6, 7
	v_lshl_or_b32 v6, v3, 3, v6
	v_lshlrev_b32_e32 v0, 4, v0
	s_ashr_i32 s69, s6, 3
	s_xor_b32 s70, s68, 15
	s_or_b32 s71, s68, 16
	s_xor_b32 s72, s68, 31
	v_add3_u32 v246, v7, v4, v8
	v_add3_u32 v247, 0, v9, v10
	v_add3_u32 v248, v5, v4, v8
	v_cmp_gt_u32_e64 s[2:3], 32, v239
	v_lshlrev_b32_e32 v249, 4, v3
	v_lshlrev_b32_e32 v250, 9, v3
	v_mov_b32_e32 v225, v224
	v_lshl_add_u64 v[226:227], s[4:5], 0, v[0:1]
	v_lshlrev_b32_e32 v228, 1, v2
	v_lshlrev_b32_e32 v230, 1, v4
	v_lshlrev_b32_e32 v252, 1, v6
	s_mov_b64 s[20:21], 0x20080
	s_mov_b64 s[22:23], 0x80000
	s_branch .LBB0_896

.LBB0_1043:
	s_setprio 0
	s_cmp_gt_i32 s63, 11
	s_cselect_b64 s[2:3], -1, 0
	s_and_b64 s[4:5], s[14:15], s[2:3]
	s_andn2_b64 vcc, exec, s[4:5]
	s_cbranch_vccnz .LBB0_1088
	s_mov_b32 s4, s1
	s_mov_b32 s5, s76
	s_waitcnt lgkmcnt(0)
	s_mov_b32 s6, s28
	s_waitcnt vmcnt(0)
	v_mbcnt_lo_u32_b32 v0, -1, 0
	v_mbcnt_hi_u32_b32 v0, -1, v0
	s_waitcnt vmcnt(0)
	s_lshl_b32 s4, s4, 6
	v_sub_u32_e32 v0, 0, v0
	v_cmp_eq_u32_e32 vcc, s4, v0
	s_barrier
	s_and_saveexec_b64 s[4:5], vcc
	s_cbranch_execz .LBB0_1087
	v_mov_b32_e32 v0, s79
	s_waitcnt vmcnt(0) expcnt(0) lgkmcnt(0)
	ds_read_b32 v2, v0
	ds_read_b32 v0, v0 offset:4
	s_waitcnt lgkmcnt(1)
	v_cmp_ne_u32_e32 vcc, 0, v2
	s_cbranch_vccnz .LBB0_1058
	v_readlane_b32 s6, v255, 0
	v_readlane_b32 s7, v255, 1
	s_load_dwordx2 s[10:11], s[6:7], 0x4
	s_add_u32 s6, s30, 0x1000
	s_addc_u32 s7, s31, 0
	s_add_u32 s8, s30, 0x1100
	s_addc_u32 s9, s31, 0
	s_waitcnt lgkmcnt(0)
	s_mul_i32 s20, s10, s28
	s_add_u32 s10, s30, 0x1200
	s_mul_i32 s20, s20, s11
	s_addc_u32 s11, s31, 0
	s_add_u32 s12, s30, 0x1300
	s_addc_u32 s13, s31, 0
	s_mov_b32 s21, 1
	v_mov_b32_e32 v16, 0
	s_branch .LBB0_1048
